# SWIGLU epilogue: gate*up products computed in place while the row-statistics loads are in flight
# baseline (speedup 1.0000x reference)
; DI unsigned pk2(float lo, float hi) { const f32x2v v = {lo, hi}; const bf16x2v b = __builtin_convertvector(v, bf16x2v); return __builtin_bit_cast(unsigned, b); }
; DI float siluf_(float x) { return x * sigmoidf_(x); }
; DI float rs_of(float ss, float inv_n) { return __builtin_amdgcn_rsqf(ss * inv_n + EPS); }
; DI float sum16_fq(const float* p, int fq) { const f32x4 a = *(const f32x4*)(p + 4 * fq); float s = (a[0] + a[1]) + (a[2] + a[3]); s += __shfl_xor(s, 16); s += __shfl_xor(s, 32); return s; }
; DI void epilogue(int kind, int l, const f32x4 (&acc)[2][2][4][2], const Unit& u, int wr, int wc, int fr, int fq) {
;     ...
;     if (E.mode == EM_SWIGLU) {
; #pragma unroll
;         for (int ai = 0; ai < 2; ++ai)
; #pragma unroll
;             for (int m = 0; m < 4; ++m) { const int row = row0 + ai * HALF + m * 16; const float rs = rs_of(sum16_fq(E.ss_in + (size_t)row * 16, fq), 1.f / 1024.f);
; #pragma unroll
;                 for (int bj = 0; bj < 2; ++bj) { const f32x4 g = acc[ai][bj][m][0] * rs, up = acc[ai][bj][m][1] * rs;
;                     u32x2 w; w.x = pk2(siluf_(g[0]) * up[0], siluf_(g[1]) * up[1]); w.y = pk2(siluf_(g[2]) * up[2], siluf_(g[3]) * up[3]);
;                     *(u32x2*)(E.o0 + (size_t)row * FF + ((col0 + bj * HALF) >> 1)) = w; } }
.LBB0_812:
	v_lshlrev_b32_e32 v24, 2, v166
	s_waitcnt lgkmcnt(0)
	v_lshl_add_u64 v[250:251], s[88:89], 0, v[24:25]
	v_ashrrev_i32_e32 v173, 31, v172
	v_lshlrev_b64 v[130:131], 6, v[172:173]
	v_lshl_add_u64 v[250:251], v[250:251], 0, v[130:131]
	v_mov_b32_e32 v252, 0x2000
	v_mov_b32_e32 v253, 0
	v_lshl_add_u64 v[252:253], v[250:251], 0, v[252:253]
	global_load_dwordx4 v[216:219], v[250:251], off
	global_load_dwordx4 v[220:223], v[250:251], off offset:1024
	global_load_dwordx4 v[224:227], v[250:251], off offset:2048
	global_load_dwordx4 v[228:231], v[250:251], off offset:3072
	global_load_dwordx4 v[232:235], v[252:253], off
	global_load_dwordx4 v[236:239], v[252:253], off offset:1024
	global_load_dwordx4 v[240:243], v[252:253], off offset:2048
	global_load_dwordx4 v[244:247], v[252:253], off offset:3072
	v_xor_b32_e32 v248, 16, v187
	v_xor_b32_e32 v249, 32, v187
	v_lshlrev_b32_e32 v248, 2, v248
	v_lshlrev_b32_e32 v249, 2, v249
	s_movk_i32 s6, 0x1600
	v_mov_b64_e32 v[130:131], s[78:79]
	v_mad_i64_i32 v[150:151], s[4:5], v172, s6, v[130:131]
	v_and_b32_e32 v24, 16, v187
	v_mul_u32_u24_e32 v24, 0x78, v24
	v_lshrrev_b32_e32 v24, 4, v24
	v_add_u32_e32 v132, v174, v24
	v_ashrrev_i32_e32 v133, 31, v132
	v_lshl_add_u64 v[150:151], v[132:133], 0, v[150:151]
	v_pk_mul_f32 v[122:123], v[126:127], v[122:123]
	v_pk_mul_f32 v[124:125], v[128:129], v[124:125]
	v_pk_mul_f32 v[106:107], v[110:111], v[106:107]
	v_pk_mul_f32 v[108:109], v[112:113], v[108:109]
	v_pk_mul_f32 v[90:91], v[94:95], v[90:91]
	v_pk_mul_f32 v[92:93], v[96:97], v[92:93]
	v_pk_mul_f32 v[74:75], v[78:79], v[74:75]
	v_pk_mul_f32 v[76:77], v[80:81], v[76:77]
	v_pk_mul_f32 v[114:115], v[118:119], v[114:115]
	v_pk_mul_f32 v[116:117], v[120:121], v[116:117]
	v_pk_mul_f32 v[98:99], v[102:103], v[98:99]
	v_pk_mul_f32 v[100:101], v[104:105], v[100:101]
	v_pk_mul_f32 v[82:83], v[86:87], v[82:83]
	v_pk_mul_f32 v[84:85], v[88:89], v[84:85]
	v_pk_mul_f32 v[66:67], v[70:71], v[66:67]
	v_pk_mul_f32 v[68:69], v[72:73], v[68:69]
	v_pk_mul_f32 v[58:59], v[62:63], v[58:59]
	v_pk_mul_f32 v[60:61], v[64:65], v[60:61]
	v_pk_mul_f32 v[42:43], v[46:47], v[42:43]
	v_pk_mul_f32 v[44:45], v[48:49], v[44:45]
	v_pk_mul_f32 v[26:27], v[30:31], v[26:27]
	v_pk_mul_f32 v[28:29], v[32:33], v[28:29]
	v_pk_mul_f32 v[8:9], v[12:13], v[8:9]
	v_pk_mul_f32 v[10:11], v[14:15], v[10:11]
	v_pk_mul_f32 v[50:51], v[54:55], v[50:51]
	v_pk_mul_f32 v[52:53], v[56:57], v[52:53]
	v_pk_mul_f32 v[34:35], v[38:39], v[34:35]
	v_pk_mul_f32 v[36:37], v[40:41], v[36:37]
	v_pk_mul_f32 v[16:17], v[20:21], v[16:17]
	v_pk_mul_f32 v[18:19], v[22:23], v[18:19]
	v_pk_mul_f32 v[0:1], v[4:5], v[0:1]
	v_pk_mul_f32 v[2:3], v[6:7], v[2:3]
	s_waitcnt vmcnt(0)
	v_add_f32_e32 v216, v217, v216
	v_add_f32_e32 v220, v221, v220
	v_add_f32_e32 v224, v225, v224
	v_add_f32_e32 v228, v229, v228
	v_add_f32_e32 v232, v233, v232
	v_add_f32_e32 v236, v237, v236
	v_add_f32_e32 v240, v241, v240
	v_add_f32_e32 v244, v245, v244
	v_add_f32_e32 v218, v218, v219
	v_add_f32_e32 v222, v222, v223
	v_add_f32_e32 v226, v226, v227
	v_add_f32_e32 v230, v230, v231
	v_add_f32_e32 v234, v234, v235
	v_add_f32_e32 v238, v238, v239
	v_add_f32_e32 v242, v242, v243
	v_add_f32_e32 v246, v246, v247
	v_add_f32_e32 v216, v216, v218
	v_add_f32_e32 v220, v220, v222
	v_add_f32_e32 v224, v224, v226
	v_add_f32_e32 v228, v228, v230
	v_add_f32_e32 v232, v232, v234
	v_add_f32_e32 v236, v236, v238
	v_add_f32_e32 v240, v240, v242
	v_add_f32_e32 v244, v244, v246
	ds_bpermute_b32 v217, v248, v216
	ds_bpermute_b32 v221, v248, v220
	ds_bpermute_b32 v225, v248, v224
	ds_bpermute_b32 v229, v248, v228
	ds_bpermute_b32 v233, v248, v232
	ds_bpermute_b32 v237, v248, v236
	ds_bpermute_b32 v241, v248, v240
	ds_bpermute_b32 v245, v248, v244
	s_waitcnt lgkmcnt(0)
	v_add_f32_e32 v216, v216, v217
	v_add_f32_e32 v220, v220, v221
	v_add_f32_e32 v224, v224, v225
	v_add_f32_e32 v228, v228, v229
	v_add_f32_e32 v232, v232, v233
	v_add_f32_e32 v236, v236, v237
	v_add_f32_e32 v240, v240, v241
	v_add_f32_e32 v244, v244, v245
	ds_bpermute_b32 v217, v249, v216
	ds_bpermute_b32 v221, v249, v220
	ds_bpermute_b32 v225, v249, v224
	ds_bpermute_b32 v229, v249, v228
	ds_bpermute_b32 v233, v249, v232
	ds_bpermute_b32 v237, v249, v236
	ds_bpermute_b32 v241, v249, v240
	ds_bpermute_b32 v245, v249, v244
	s_waitcnt lgkmcnt(0)
; DI unsigned pk2(float lo, float hi) { const f32x2v v = {lo, hi}; const bf16x2v b = __builtin_convertvector(v, bf16x2v); return __builtin_bit_cast(unsigned, b); }
; DI float rs_of(float ss, float inv_n) { return __builtin_amdgcn_rsqf(ss * inv_n + EPS); }
; DI float sum16_fq(const float* p, int fq) { const f32x4 a = *(const f32x4*)(p + 4 * fq); float s = (a[0] + a[1]) + (a[2] + a[3]); s += __shfl_xor(s, 16); s += __shfl_xor(s, 32); return s; }
; DI float sigmoidf_(float x) { return __builtin_amdgcn_rcpf(1.0f + __expf(-x)); }
; DI float siluf_(float x) { return x * sigmoidf_(x); }
; DI void epilogue(int kind, int l, const f32x4 (&acc)[2][2][4][2], const Unit& u, int wr, int wc, int fr, int fq) {
;     ...
;             for (int m = 0; m < 4; ++m) { const int row = row0 + ai * HALF + m * 16; const float rs = rs_of(sum16_fq(E.ss_in + (size_t)row * 16, fq), 1.f / 1024.f);
; #pragma unroll
;                 for (int bj = 0; bj < 2; ++bj) { const f32x4 g = acc[ai][bj][m][0] * rs, up = acc[ai][bj][m][1] * rs;
;                     u32x2 w; w.x = pk2(siluf_(g[0]) * up[0], siluf_(g[1]) * up[1]); w.y = pk2(siluf_(g[2]) * up[2], siluf_(g[3]) * up[3]);
;                     *(u32x2*)(E.o0 + (size_t)row * FF + ((col0 + bj * HALF) >> 1)) = w; } }
	v_add_f32_e32 v216, v216, v217
	v_add_f32_e32 v220, v220, v221
	v_add_f32_e32 v224, v224, v225
	v_add_f32_e32 v228, v228, v229
	v_add_f32_e32 v232, v232, v233
	v_add_f32_e32 v236, v236, v237
	v_add_f32_e32 v240, v240, v241
	v_add_f32_e32 v244, v244, v245
	v_fmamk_f32 v216, v216, 0x3a800000, v185
	v_fmamk_f32 v220, v220, 0x3a800000, v185
	v_fmamk_f32 v224, v224, 0x3a800000, v185
	v_fmamk_f32 v228, v228, 0x3a800000, v185
	v_fmamk_f32 v232, v232, 0x3a800000, v185
	v_fmamk_f32 v236, v236, 0x3a800000, v185
	v_fmamk_f32 v240, v240, 0x3a800000, v185
	v_fmamk_f32 v244, v244, 0x3a800000, v185
	v_rsq_f32_e32 v216, v216
	v_rsq_f32_e32 v220, v220
	v_rsq_f32_e32 v224, v224
	v_rsq_f32_e32 v228, v228
	v_rsq_f32_e32 v232, v232
	v_rsq_f32_e32 v236, v236
	v_rsq_f32_e32 v240, v240
	v_rsq_f32_e32 v244, v244
	v_mul_f32_e32 v217, 0xbfb8aa3b, v216
	v_mul_f32_e32 v221, 0xbfb8aa3b, v220
	v_mul_f32_e32 v225, 0xbfb8aa3b, v224
	v_mul_f32_e32 v229, 0xbfb8aa3b, v228
	v_mul_f32_e32 v233, 0xbfb8aa3b, v232
	v_mul_f32_e32 v237, 0xbfb8aa3b, v236
	v_mul_f32_e32 v241, 0xbfb8aa3b, v240
	v_mul_f32_e32 v245, 0xbfb8aa3b, v244
	v_mul_f32_e32 v218, v216, v216
	v_mul_f32_e32 v222, v220, v220
	v_mul_f32_e32 v226, v224, v224
	v_mul_f32_e32 v230, v228, v228
	v_mul_f32_e32 v234, v232, v232
	v_mul_f32_e32 v238, v236, v236
	v_mul_f32_e32 v242, v240, v240
	v_mul_f32_e32 v246, v244, v244
	v_mul_f32_e32 v130, v126, v217
	v_mul_f32_e32 v131, v127, v217
	v_mul_f32_e32 v132, v128, v217
	v_mul_f32_e32 v133, v129, v217
	v_exp_f32_e32 v130, v130
	v_exp_f32_e32 v131, v131
	v_exp_f32_e32 v132, v132
	v_exp_f32_e32 v133, v133
	v_add_f32_e32 v130, 1.0, v130
	v_add_f32_e32 v131, 1.0, v131
	v_add_f32_e32 v132, 1.0, v132
	v_add_f32_e32 v133, 1.0, v133
	v_rcp_f32_e32 v130, v130
	v_rcp_f32_e32 v131, v131
	v_rcp_f32_e32 v132, v132
	v_rcp_f32_e32 v133, v133
	v_pk_mul_f32 v[130:131], v[130:131], v[218:219] op_sel_hi:[1,0]
	v_pk_mul_f32 v[132:133], v[132:133], v[218:219] op_sel_hi:[1,0]
	v_pk_mul_f32 v[134:135], v[122:123], v[130:131]
	v_pk_mul_f32 v[136:137], v[124:125], v[132:133]
	v_cvt_pk_bf16_f32 v138, v134, v135
	v_cvt_pk_bf16_f32 v139, v136, v137
	v_mul_f32_e32 v130, v118, v217
	v_mul_f32_e32 v131, v119, v217
	v_mul_f32_e32 v132, v120, v217
	v_mul_f32_e32 v133, v121, v217
	v_exp_f32_e32 v130, v130
	v_exp_f32_e32 v131, v131
	v_exp_f32_e32 v132, v132
	v_exp_f32_e32 v133, v133
	v_add_f32_e32 v130, 1.0, v130
	v_add_f32_e32 v131, 1.0, v131
	v_add_f32_e32 v132, 1.0, v132
	v_add_f32_e32 v133, 1.0, v133
	v_rcp_f32_e32 v130, v130
	v_rcp_f32_e32 v131, v131
	v_rcp_f32_e32 v132, v132
	v_rcp_f32_e32 v133, v133
	v_pk_mul_f32 v[130:131], v[130:131], v[218:219] op_sel_hi:[1,0]
	v_pk_mul_f32 v[132:133], v[132:133], v[218:219] op_sel_hi:[1,0]
	v_pk_mul_f32 v[134:135], v[114:115], v[130:131]
	v_pk_mul_f32 v[136:137], v[116:117], v[132:133]
	v_cvt_pk_bf16_f32 v140, v134, v135
	v_cvt_pk_bf16_f32 v141, v136, v137
	s_nop 1
	v_permlane16_swap_b32_e32 v138, v140
	v_permlane16_swap_b32_e32 v139, v141
	global_store_dwordx4 v[150:151], v[138:141], off
	v_add_co_u32_e32 v150, vcc, 0x16000, v150
	s_nop 1
	v_addc_co_u32_e32 v151, vcc, 0, v151, vcc
	v_mul_f32_e32 v130, v110, v221
	v_mul_f32_e32 v131, v111, v221
	v_mul_f32_e32 v132, v112, v221
	v_mul_f32_e32 v133, v113, v221
	v_exp_f32_e32 v130, v130
	v_exp_f32_e32 v131, v131
	v_exp_f32_e32 v132, v132
	v_exp_f32_e32 v133, v133
	v_add_f32_e32 v130, 1.0, v130
	v_add_f32_e32 v131, 1.0, v131
	v_add_f32_e32 v132, 1.0, v132
	v_add_f32_e32 v133, 1.0, v133
	v_rcp_f32_e32 v130, v130
	v_rcp_f32_e32 v131, v131
	v_rcp_f32_e32 v132, v132
	v_rcp_f32_e32 v133, v133
	v_pk_mul_f32 v[130:131], v[130:131], v[222:223] op_sel_hi:[1,0]
	v_pk_mul_f32 v[132:133], v[132:133], v[222:223] op_sel_hi:[1,0]
	v_pk_mul_f32 v[134:135], v[106:107], v[130:131]
	v_pk_mul_f32 v[136:137], v[108:109], v[132:133]
	v_cvt_pk_bf16_f32 v142, v134, v135
	v_cvt_pk_bf16_f32 v143, v136, v137
	v_mul_f32_e32 v130, v102, v221
	v_mul_f32_e32 v131, v103, v221
	v_mul_f32_e32 v132, v104, v221
	v_mul_f32_e32 v133, v105, v221
	v_exp_f32_e32 v130, v130
	v_exp_f32_e32 v131, v131
	v_exp_f32_e32 v132, v132
	v_exp_f32_e32 v133, v133
	v_add_f32_e32 v130, 1.0, v130
	v_add_f32_e32 v131, 1.0, v131
	v_add_f32_e32 v132, 1.0, v132
	v_add_f32_e32 v133, 1.0, v133
	v_rcp_f32_e32 v130, v130
	v_rcp_f32_e32 v131, v131
	v_rcp_f32_e32 v132, v132
	v_rcp_f32_e32 v133, v133
	v_pk_mul_f32 v[130:131], v[130:131], v[222:223] op_sel_hi:[1,0]
	v_pk_mul_f32 v[132:133], v[132:133], v[222:223] op_sel_hi:[1,0]
	v_pk_mul_f32 v[134:135], v[98:99], v[130:131]
	v_pk_mul_f32 v[136:137], v[100:101], v[132:133]
	v_cvt_pk_bf16_f32 v144, v134, v135
	v_cvt_pk_bf16_f32 v145, v136, v137
	s_nop 1
	v_permlane16_swap_b32_e32 v142, v144
	v_permlane16_swap_b32_e32 v143, v145
	global_store_dwordx4 v[150:151], v[142:145], off
	v_add_co_u32_e32 v150, vcc, 0x16000, v150
	s_nop 1
	v_addc_co_u32_e32 v151, vcc, 0, v151, vcc
	v_mul_f32_e32 v130, v94, v225
	v_mul_f32_e32 v131, v95, v225
	v_mul_f32_e32 v132, v96, v225
	v_mul_f32_e32 v133, v97, v225
	v_exp_f32_e32 v130, v130
	v_exp_f32_e32 v131, v131
	v_exp_f32_e32 v132, v132
	v_exp_f32_e32 v133, v133
	v_add_f32_e32 v130, 1.0, v130
	v_add_f32_e32 v131, 1.0, v131
	v_add_f32_e32 v132, 1.0, v132
	v_add_f32_e32 v133, 1.0, v133
	v_rcp_f32_e32 v130, v130
	v_rcp_f32_e32 v131, v131
	v_rcp_f32_e32 v132, v132
	v_rcp_f32_e32 v133, v133
	v_pk_mul_f32 v[130:131], v[130:131], v[226:227] op_sel_hi:[1,0]
	v_pk_mul_f32 v[132:133], v[132:133], v[226:227] op_sel_hi:[1,0]
	v_pk_mul_f32 v[134:135], v[90:91], v[130:131]
	v_pk_mul_f32 v[136:137], v[92:93], v[132:133]
	v_cvt_pk_bf16_f32 v138, v134, v135
	v_cvt_pk_bf16_f32 v139, v136, v137
	v_mul_f32_e32 v130, v86, v225
; DI unsigned pk2(float lo, float hi) { const f32x2v v = {lo, hi}; const bf16x2v b = __builtin_convertvector(v, bf16x2v); return __builtin_bit_cast(unsigned, b); }
; DI float rs_of(float ss, float inv_n) { return __builtin_amdgcn_rsqf(ss * inv_n + EPS); }
; DI float sum16_fq(const float* p, int fq) { const f32x4 a = *(const f32x4*)(p + 4 * fq); float s = (a[0] + a[1]) + (a[2] + a[3]); s += __shfl_xor(s, 16); s += __shfl_xor(s, 32); return s; }
; DI float sigmoidf_(float x) { return __builtin_amdgcn_rcpf(1.0f + __expf(-x)); }
; DI float siluf_(float x) { return x * sigmoidf_(x); }
; DI void epilogue(int kind, int l, const f32x4 (&acc)[2][2][4][2], const Unit& u, int wr, int wc, int fr, int fq) {
;     ...
;             for (int m = 0; m < 4; ++m) { const int row = row0 + ai * HALF + m * 16; const float rs = rs_of(sum16_fq(E.ss_in + (size_t)row * 16, fq), 1.f / 1024.f);
; #pragma unroll
;                 for (int bj = 0; bj < 2; ++bj) { const f32x4 g = acc[ai][bj][m][0] * rs, up = acc[ai][bj][m][1] * rs;
;                     u32x2 w; w.x = pk2(siluf_(g[0]) * up[0], siluf_(g[1]) * up[1]); w.y = pk2(siluf_(g[2]) * up[2], siluf_(g[3]) * up[3]);
;                     *(u32x2*)(E.o0 + (size_t)row * FF + ((col0 + bj * HALF) >> 1)) = w; } }
	v_mul_f32_e32 v131, v87, v225
	v_mul_f32_e32 v132, v88, v225
	v_mul_f32_e32 v133, v89, v225
	v_exp_f32_e32 v130, v130
	v_exp_f32_e32 v131, v131
	v_exp_f32_e32 v132, v132
	v_exp_f32_e32 v133, v133
	v_add_f32_e32 v130, 1.0, v130
	v_add_f32_e32 v131, 1.0, v131
	v_add_f32_e32 v132, 1.0, v132
	v_add_f32_e32 v133, 1.0, v133
	v_rcp_f32_e32 v130, v130
	v_rcp_f32_e32 v131, v131
	v_rcp_f32_e32 v132, v132
	v_rcp_f32_e32 v133, v133
	v_pk_mul_f32 v[130:131], v[130:131], v[226:227] op_sel_hi:[1,0]
	v_pk_mul_f32 v[132:133], v[132:133], v[226:227] op_sel_hi:[1,0]
	v_pk_mul_f32 v[134:135], v[82:83], v[130:131]
	v_pk_mul_f32 v[136:137], v[84:85], v[132:133]
	v_cvt_pk_bf16_f32 v140, v134, v135
	v_cvt_pk_bf16_f32 v141, v136, v137
	s_nop 1
	v_permlane16_swap_b32_e32 v138, v140
	v_permlane16_swap_b32_e32 v139, v141
	global_store_dwordx4 v[150:151], v[138:141], off
	v_add_co_u32_e32 v150, vcc, 0x16000, v150
	s_nop 1
	v_addc_co_u32_e32 v151, vcc, 0, v151, vcc
	v_mul_f32_e32 v130, v78, v229
	v_mul_f32_e32 v131, v79, v229
	v_mul_f32_e32 v132, v80, v229
	v_mul_f32_e32 v133, v81, v229
	v_exp_f32_e32 v130, v130
	v_exp_f32_e32 v131, v131
	v_exp_f32_e32 v132, v132
	v_exp_f32_e32 v133, v133
	v_add_f32_e32 v130, 1.0, v130
	v_add_f32_e32 v131, 1.0, v131
	v_add_f32_e32 v132, 1.0, v132
	v_add_f32_e32 v133, 1.0, v133
	v_rcp_f32_e32 v130, v130
	v_rcp_f32_e32 v131, v131
	v_rcp_f32_e32 v132, v132
	v_rcp_f32_e32 v133, v133
	v_pk_mul_f32 v[130:131], v[130:131], v[230:231] op_sel_hi:[1,0]
	v_pk_mul_f32 v[132:133], v[132:133], v[230:231] op_sel_hi:[1,0]
	v_pk_mul_f32 v[134:135], v[74:75], v[130:131]
	v_pk_mul_f32 v[136:137], v[76:77], v[132:133]
	v_cvt_pk_bf16_f32 v142, v134, v135
	v_cvt_pk_bf16_f32 v143, v136, v137
	v_mul_f32_e32 v130, v70, v229
	v_mul_f32_e32 v131, v71, v229
	v_mul_f32_e32 v132, v72, v229
	v_mul_f32_e32 v133, v73, v229
	v_exp_f32_e32 v130, v130
	v_exp_f32_e32 v131, v131
	v_exp_f32_e32 v132, v132
	v_exp_f32_e32 v133, v133
	v_add_f32_e32 v130, 1.0, v130
	v_add_f32_e32 v131, 1.0, v131
	v_add_f32_e32 v132, 1.0, v132
	v_add_f32_e32 v133, 1.0, v133
	v_rcp_f32_e32 v130, v130
	v_rcp_f32_e32 v131, v131
	v_rcp_f32_e32 v132, v132
	v_rcp_f32_e32 v133, v133
	v_pk_mul_f32 v[130:131], v[130:131], v[230:231] op_sel_hi:[1,0]
	v_pk_mul_f32 v[132:133], v[132:133], v[230:231] op_sel_hi:[1,0]
	v_pk_mul_f32 v[134:135], v[66:67], v[130:131]
	v_pk_mul_f32 v[136:137], v[68:69], v[132:133]
	v_cvt_pk_bf16_f32 v144, v134, v135
	v_cvt_pk_bf16_f32 v145, v136, v137
	s_nop 1
	v_permlane16_swap_b32_e32 v142, v144
	v_permlane16_swap_b32_e32 v143, v145
	global_store_dwordx4 v[150:151], v[142:145], off
	v_add_co_u32_e32 v150, vcc, 0x6e000, v150
	s_nop 1
	v_addc_co_u32_e32 v151, vcc, 0, v151, vcc
	v_mul_f32_e32 v130, v62, v233
	v_mul_f32_e32 v131, v63, v233
	v_mul_f32_e32 v132, v64, v233
	v_mul_f32_e32 v133, v65, v233
	v_exp_f32_e32 v130, v130
	v_exp_f32_e32 v131, v131
	v_exp_f32_e32 v132, v132
	v_exp_f32_e32 v133, v133
	v_add_f32_e32 v130, 1.0, v130
	v_add_f32_e32 v131, 1.0, v131
	v_add_f32_e32 v132, 1.0, v132
	v_add_f32_e32 v133, 1.0, v133
	v_rcp_f32_e32 v130, v130
	v_rcp_f32_e32 v131, v131
	v_rcp_f32_e32 v132, v132
	v_rcp_f32_e32 v133, v133
	v_pk_mul_f32 v[130:131], v[130:131], v[234:235] op_sel_hi:[1,0]
	v_pk_mul_f32 v[132:133], v[132:133], v[234:235] op_sel_hi:[1,0]
	v_pk_mul_f32 v[134:135], v[58:59], v[130:131]
	v_pk_mul_f32 v[136:137], v[60:61], v[132:133]
	v_cvt_pk_bf16_f32 v138, v134, v135
	v_cvt_pk_bf16_f32 v139, v136, v137
	v_mul_f32_e32 v130, v54, v233
	v_mul_f32_e32 v131, v55, v233
	v_mul_f32_e32 v132, v56, v233
	v_mul_f32_e32 v133, v57, v233
	v_exp_f32_e32 v130, v130
	v_exp_f32_e32 v131, v131
	v_exp_f32_e32 v132, v132
	v_exp_f32_e32 v133, v133
	v_add_f32_e32 v130, 1.0, v130
	v_add_f32_e32 v131, 1.0, v131
	v_add_f32_e32 v132, 1.0, v132
	v_add_f32_e32 v133, 1.0, v133
	v_rcp_f32_e32 v130, v130
	v_rcp_f32_e32 v131, v131
	v_rcp_f32_e32 v132, v132
	v_rcp_f32_e32 v133, v133
	v_pk_mul_f32 v[130:131], v[130:131], v[234:235] op_sel_hi:[1,0]
	v_pk_mul_f32 v[132:133], v[132:133], v[234:235] op_sel_hi:[1,0]
	v_pk_mul_f32 v[134:135], v[50:51], v[130:131]
	v_pk_mul_f32 v[136:137], v[52:53], v[132:133]
	v_cvt_pk_bf16_f32 v140, v134, v135
	v_cvt_pk_bf16_f32 v141, v136, v137
	s_nop 1
	v_permlane16_swap_b32_e32 v138, v140
	v_permlane16_swap_b32_e32 v139, v141
	global_store_dwordx4 v[150:151], v[138:141], off
	v_add_co_u32_e32 v150, vcc, 0x16000, v150
	s_nop 1
	v_addc_co_u32_e32 v151, vcc, 0, v151, vcc
	v_mul_f32_e32 v130, v46, v237
	v_mul_f32_e32 v131, v47, v237
	v_mul_f32_e32 v132, v48, v237
	v_mul_f32_e32 v133, v49, v237
	v_exp_f32_e32 v130, v130
	v_exp_f32_e32 v131, v131
	v_exp_f32_e32 v132, v132
	v_exp_f32_e32 v133, v133
	v_add_f32_e32 v130, 1.0, v130
	v_add_f32_e32 v131, 1.0, v131
	v_add_f32_e32 v132, 1.0, v132
	v_add_f32_e32 v133, 1.0, v133
; DI unsigned pk2(float lo, float hi) { const f32x2v v = {lo, hi}; const bf16x2v b = __builtin_convertvector(v, bf16x2v); return __builtin_bit_cast(unsigned, b); }
; DI float rs_of(float ss, float inv_n) { return __builtin_amdgcn_rsqf(ss * inv_n + EPS); }
; DI float sum16_fq(const float* p, int fq) { const f32x4 a = *(const f32x4*)(p + 4 * fq); float s = (a[0] + a[1]) + (a[2] + a[3]); s += __shfl_xor(s, 16); s += __shfl_xor(s, 32); return s; }
; DI float sigmoidf_(float x) { return __builtin_amdgcn_rcpf(1.0f + __expf(-x)); }
; DI float siluf_(float x) { return x * sigmoidf_(x); }
; DI void epilogue(int kind, int l, const f32x4 (&acc)[2][2][4][2], const Unit& u, int wr, int wc, int fr, int fq) {
;     ...
;             for (int m = 0; m < 4; ++m) { const int row = row0 + ai * HALF + m * 16; const float rs = rs_of(sum16_fq(E.ss_in + (size_t)row * 16, fq), 1.f / 1024.f);
; #pragma unroll
;                 for (int bj = 0; bj < 2; ++bj) { const f32x4 g = acc[ai][bj][m][0] * rs, up = acc[ai][bj][m][1] * rs;
;                     u32x2 w; w.x = pk2(siluf_(g[0]) * up[0], siluf_(g[1]) * up[1]); w.y = pk2(siluf_(g[2]) * up[2], siluf_(g[3]) * up[3]);
;                     *(u32x2*)(E.o0 + (size_t)row * FF + ((col0 + bj * HALF) >> 1)) = w; } }
	v_rcp_f32_e32 v130, v130
	v_rcp_f32_e32 v131, v131
	v_rcp_f32_e32 v132, v132
	v_rcp_f32_e32 v133, v133
	v_pk_mul_f32 v[130:131], v[130:131], v[238:239] op_sel_hi:[1,0]
	v_pk_mul_f32 v[132:133], v[132:133], v[238:239] op_sel_hi:[1,0]
	v_pk_mul_f32 v[134:135], v[42:43], v[130:131]
	v_pk_mul_f32 v[136:137], v[44:45], v[132:133]
	v_cvt_pk_bf16_f32 v142, v134, v135
	v_cvt_pk_bf16_f32 v143, v136, v137
	v_mul_f32_e32 v130, v38, v237
	v_mul_f32_e32 v131, v39, v237
	v_mul_f32_e32 v132, v40, v237
	v_mul_f32_e32 v133, v41, v237
	v_exp_f32_e32 v130, v130
	v_exp_f32_e32 v131, v131
	v_exp_f32_e32 v132, v132
	v_exp_f32_e32 v133, v133
	v_add_f32_e32 v130, 1.0, v130
	v_add_f32_e32 v131, 1.0, v131
	v_add_f32_e32 v132, 1.0, v132
	v_add_f32_e32 v133, 1.0, v133
	v_rcp_f32_e32 v130, v130
	v_rcp_f32_e32 v131, v131
	v_rcp_f32_e32 v132, v132
	v_rcp_f32_e32 v133, v133
	v_pk_mul_f32 v[130:131], v[130:131], v[238:239] op_sel_hi:[1,0]
	v_pk_mul_f32 v[132:133], v[132:133], v[238:239] op_sel_hi:[1,0]
	v_pk_mul_f32 v[134:135], v[34:35], v[130:131]
	v_pk_mul_f32 v[136:137], v[36:37], v[132:133]
	v_cvt_pk_bf16_f32 v144, v134, v135
	v_cvt_pk_bf16_f32 v145, v136, v137
	s_nop 1
	v_permlane16_swap_b32_e32 v142, v144
	v_permlane16_swap_b32_e32 v143, v145
	global_store_dwordx4 v[150:151], v[142:145], off
	v_add_co_u32_e32 v150, vcc, 0x16000, v150
	s_nop 1
	v_addc_co_u32_e32 v151, vcc, 0, v151, vcc
	v_mul_f32_e32 v130, v30, v241
	v_mul_f32_e32 v131, v31, v241
	v_mul_f32_e32 v132, v32, v241
	v_mul_f32_e32 v133, v33, v241
	v_exp_f32_e32 v130, v130
	v_exp_f32_e32 v131, v131
	v_exp_f32_e32 v132, v132
	v_exp_f32_e32 v133, v133
	v_add_f32_e32 v130, 1.0, v130
	v_add_f32_e32 v131, 1.0, v131
	v_add_f32_e32 v132, 1.0, v132
	v_add_f32_e32 v133, 1.0, v133
	v_rcp_f32_e32 v130, v130
	v_rcp_f32_e32 v131, v131
	v_rcp_f32_e32 v132, v132
	v_rcp_f32_e32 v133, v133
	v_pk_mul_f32 v[130:131], v[130:131], v[242:243] op_sel_hi:[1,0]
	v_pk_mul_f32 v[132:133], v[132:133], v[242:243] op_sel_hi:[1,0]
	v_pk_mul_f32 v[134:135], v[26:27], v[130:131]
	v_pk_mul_f32 v[136:137], v[28:29], v[132:133]
	v_cvt_pk_bf16_f32 v138, v134, v135
	v_cvt_pk_bf16_f32 v139, v136, v137
	v_mul_f32_e32 v130, v20, v241
	v_mul_f32_e32 v131, v21, v241
	v_mul_f32_e32 v132, v22, v241
	v_mul_f32_e32 v133, v23, v241
	v_exp_f32_e32 v130, v130
	v_exp_f32_e32 v131, v131
	v_exp_f32_e32 v132, v132
	v_exp_f32_e32 v133, v133
	v_add_f32_e32 v130, 1.0, v130
	v_add_f32_e32 v131, 1.0, v131
	v_add_f32_e32 v132, 1.0, v132
	v_add_f32_e32 v133, 1.0, v133
	v_rcp_f32_e32 v130, v130
	v_rcp_f32_e32 v131, v131
	v_rcp_f32_e32 v132, v132
	v_rcp_f32_e32 v133, v133
	v_pk_mul_f32 v[130:131], v[130:131], v[242:243] op_sel_hi:[1,0]
	v_pk_mul_f32 v[132:133], v[132:133], v[242:243] op_sel_hi:[1,0]
	v_pk_mul_f32 v[134:135], v[16:17], v[130:131]
	v_pk_mul_f32 v[136:137], v[18:19], v[132:133]
	v_cvt_pk_bf16_f32 v140, v134, v135
	v_cvt_pk_bf16_f32 v141, v136, v137
	s_nop 1
	v_permlane16_swap_b32_e32 v138, v140
	v_permlane16_swap_b32_e32 v139, v141
	global_store_dwordx4 v[150:151], v[138:141], off
	v_add_co_u32_e32 v150, vcc, 0x16000, v150
	s_nop 1
	v_addc_co_u32_e32 v151, vcc, 0, v151, vcc
	v_mul_f32_e32 v130, v12, v245
	v_mul_f32_e32 v131, v13, v245
	v_mul_f32_e32 v132, v14, v245
	v_mul_f32_e32 v133, v15, v245
	v_exp_f32_e32 v130, v130
	v_exp_f32_e32 v131, v131
	v_exp_f32_e32 v132, v132
	v_exp_f32_e32 v133, v133
	v_add_f32_e32 v130, 1.0, v130
	v_add_f32_e32 v131, 1.0, v131
	v_add_f32_e32 v132, 1.0, v132
	v_add_f32_e32 v133, 1.0, v133
	v_rcp_f32_e32 v130, v130
	v_rcp_f32_e32 v131, v131
	v_rcp_f32_e32 v132, v132
	v_rcp_f32_e32 v133, v133
	v_pk_mul_f32 v[130:131], v[130:131], v[246:247] op_sel_hi:[1,0]
	v_pk_mul_f32 v[132:133], v[132:133], v[246:247] op_sel_hi:[1,0]
	v_pk_mul_f32 v[134:135], v[8:9], v[130:131]
	v_pk_mul_f32 v[136:137], v[10:11], v[132:133]
	v_cvt_pk_bf16_f32 v142, v134, v135
	v_cvt_pk_bf16_f32 v143, v136, v137
	v_mul_f32_e32 v130, v4, v245
	v_mul_f32_e32 v131, v5, v245
	v_mul_f32_e32 v132, v6, v245
	v_mul_f32_e32 v133, v7, v245
	v_exp_f32_e32 v130, v130
	v_exp_f32_e32 v131, v131
	v_exp_f32_e32 v132, v132
	v_exp_f32_e32 v133, v133
	v_add_f32_e32 v130, 1.0, v130
	v_add_f32_e32 v131, 1.0, v131
	v_add_f32_e32 v132, 1.0, v132
	v_add_f32_e32 v133, 1.0, v133
	v_rcp_f32_e32 v130, v130
	v_rcp_f32_e32 v131, v131
	v_rcp_f32_e32 v132, v132
	v_rcp_f32_e32 v133, v133
	v_pk_mul_f32 v[130:131], v[130:131], v[246:247] op_sel_hi:[1,0]
	v_pk_mul_f32 v[132:133], v[132:133], v[246:247] op_sel_hi:[1,0]
	v_pk_mul_f32 v[134:135], v[0:1], v[130:131]
	v_pk_mul_f32 v[136:137], v[2:3], v[132:133]
	v_cvt_pk_bf16_f32 v144, v134, v135
	v_cvt_pk_bf16_f32 v145, v136, v137
	s_nop 1
	v_permlane16_swap_b32_e32 v142, v144
	v_permlane16_swap_b32_e32 v143, v145
	global_store_dwordx4 v[150:151], v[142:145], off
